# A-attention pipelined loop: softmax row sums moved from 32x32x16 ones-MFMA to 4x4x4 bf16 MFMA (2-pass), f32 accumulate kept
# speedup vs baseline: 1.0211x; 1.0007x over previous
; #define LAS __attribute__((address_space(3)))
; template <bool TRACK> ...
;     ...
;             for (int d = 0; d < 4; ++d) { kf[2 * d] = *(const LAS bf16x8*)(Kbuf + (r32 * 72 + d * 16 + hi * 8) * 2); kf[2 * d + 1] = *(const LAS bf16x8*)(Kbuf + ((32 + r32) * 72 + d * 16 + hi * 8) * 2); }
;             __builtin_amdgcn_sched_barrier(0);
; #pragma unroll
;             for (int d = 0; d < 4; ++d) {
;                 s0 = __builtin_amdgcn_mfma_f32_32x32x16_bf16(kf[2 * d], qf[d], s0, 0, 0, 0);
;                 s1 = __builtin_amdgcn_mfma_f32_32x32x16_bf16(kf[2 * d + 1], qf[d], s1, 0, 0, 0);
;             }
; #pragma unroll
;             for (int kc = 0; kc < 2; ++kc) {
;                 const LAS unsigned char* vp0 = Vbuf + (r32 * 68 + kc * 16 + 4 * hi) * 2; const LAS unsigned char* vp1 = vp0 + 32 * 68 * 2;
;                 vq[4 * kc] = *(const LAS u32x2*)vp0; vq[4 * kc + 1] = *(const LAS u32x2*)(vp0 + 16); vq[4 * kc + 2] = *(const LAS u32x2*)vp1; vq[4 * kc + 3] = *(const LAS u32x2*)(vp1 + 16); }
;             __builtin_amdgcn_sched_barrier(0);
;             } else {
; #pragma unroll
;             for (int d = 0; d < 4; ++d) {
;                 const bf16x8 a0 = *(const LAS bf16x8*)(Kbuf + (r32 * 72 + d * 16 + hi * 8) * 2);
;                 const bf16x8 a1 = *(const LAS bf16x8*)(Kbuf + ((32 + r32) * 72 + d * 16 + hi * 8) * 2);
;                 s0 = __builtin_amdgcn_mfma_f32_32x32x16_bf16(a0, qf[d], s0, 0, 0, 0);
;                 s1 = __builtin_amdgcn_mfma_f32_32x32x16_bf16(a1, qf[d], s1, 0, 0, 0);
;             }
;             }
;             if (mt) { const int qpos = qstart + wave * 32 + r32;
; #pragma unroll
;                 for (int r = 0; r < 16; ++r) { const int d0 = qpos - (kpos0 + crow(r, hi)); if (d0 > 128 || d0 < -128) s0[r] = -INFINITY; const int d1 = d0 - 32; if (d1 > 128 || d1 < -128) s1[r] = -INFINITY; } }
;             if (TRACK) {
;             float mx = fmaxf(fmaxf(s0[0], s1[0]), s0[1]);
; #pragma unroll
;             for (int r = 1; r < 15; r += 2) mx = fmaxf(fmaxf(mx, s1[r]), fmaxf(fmaxf(s0[r + 1], s1[r + 1]), s0[r + 2 < 16 ? r + 2 : 15]));
;             mx = fmaxf(mx, s1[15]);
;             mx = fmaxf(mx, __shfl_xor(mx, 32));
;             if (__any(mx > ATT_THR)) {
;                 const float dl = fmaxf(mx, 0.f); m += dl; const float alpha = __builtin_amdgcn_exp2f(-dl); lsum *= alpha;
; #pragma unroll
.LBB0_167:
	global_load_dwordx4 v[98:101], v[114:115], off
	global_load_dwordx4 v[102:105], v[116:117], off
	ds_read_b128 v[106:109], v204 offset:18432
	ds_read_b128 v[110:113], v202 offset:18432
	ds_read_b128 v[158:161], v204 offset:18464
	ds_read2_b64 v[206:209], v247 offset0:128 offset1:130
	ds_read2_b64 v[210:213], v0 offset0:160 offset1:162
	v_lshl_add_u64 v[114:115], v[114:115], 0, s[4:5]
	v_lshl_add_u64 v[116:117], v[116:117], 0, s[38:39]
	s_waitcnt lgkmcnt(4)
	v_mfma_f32_32x32x16_bf16 v[214:229], v[106:109], v[94:97], 0
	ds_read_b128 v[106:109], v202 offset:18464
	v_exp_f32_e32 v58, v58
	v_exp_f32_e32 v59, v59
	v_exp_f32_e32 v60, v60
	s_waitcnt lgkmcnt(4)
	v_mfma_f32_32x32x16_bf16 v[230:245], v[110:113], v[94:97], 0
	ds_read_b128 v[110:113], v204 offset:18496
	v_exp_f32_e32 v61, v61
	v_exp_f32_e32 v62, v62
	v_exp_f32_e32 v63, v63
	s_waitcnt lgkmcnt(4)
	v_mfma_f32_32x32x16_bf16 v[214:229], v[158:161], v[90:93], v[214:229]
	ds_read_b128 v[158:161], v202 offset:18496
	v_exp_f32_e32 v64, v64
	v_exp_f32_e32 v65, v65
	v_cvt_pk_bf16_f32 v54, v58, v59
	s_waitcnt lgkmcnt(2)
	v_mfma_f32_32x32x16_bf16 v[230:245], v[106:109], v[90:93], v[230:245]
	ds_read_b128 v[106:109], v204 offset:18528
	v_cvt_pk_bf16_f32 v55, v60, v61
	v_cvt_pk_bf16_f32 v56, v62, v63
	v_cvt_pk_bf16_f32 v57, v64, v65
	s_waitcnt lgkmcnt(2)
	v_mfma_f32_32x32x16_bf16 v[214:229], v[110:113], v[86:89], v[214:229]
	ds_read_b128 v[110:113], v202 offset:18528
	v_exp_f32_e32 v66, v66
	v_exp_f32_e32 v67, v67
	v_exp_f32_e32 v68, v68
	s_waitcnt lgkmcnt(2)
	v_mfma_f32_32x32x16_bf16 v[230:245], v[158:161], v[86:89], v[230:245]
	v_exp_f32_e32 v69, v69
	v_exp_f32_e32 v70, v70
	v_exp_f32_e32 v71, v71
	s_waitcnt lgkmcnt(1)
	v_mfma_f32_32x32x16_bf16 v[214:229], v[106:109], v[82:85], v[214:229]
	v_exp_f32_e32 v72, v72
	v_exp_f32_e32 v73, v73
	v_cvt_pk_bf16_f32 v66, v66, v67
	s_waitcnt lgkmcnt(0)
	v_mfma_f32_32x32x16_bf16 v[230:245], v[110:113], v[82:85], v[230:245]
	v_cvt_pk_bf16_f32 v67, v68, v69
	v_cvt_pk_bf16_f32 v68, v70, v71
	v_cvt_pk_bf16_f32 v69, v72, v73
	v_mfma_f32_32x32x16_bf16 v[2:17], v[206:209], v[50:53], v[2:17]
	ds_read2_b64 v[206:209], v247 offset0:132 offset1:134
	v_exp_f32_e32 v74, v74
	v_exp_f32_e32 v75, v75
	v_exp_f32_e32 v76, v76
	v_mfma_f32_32x32x16_bf16 v[18:33], v[210:213], v[50:53], v[18:33]
	ds_read2_b64 v[210:213], v0 offset0:164 offset1:166
	v_exp_f32_e32 v77, v77
	v_exp_f32_e32 v78, v78
	v_exp_f32_e32 v79, v79
	v_mfma_f32_4x4x4_16b_bf16 v[34:37], v[118:119], v[50:51], v[34:37]
	v_mfma_f32_4x4x4_16b_bf16 v[38:41], v[118:119], v[52:53], v[38:41]
	v_exp_f32_e32 v80, v80
	v_exp_f32_e32 v81, v81
	s_waitcnt lgkmcnt(1)
	v_mfma_f32_32x32x16_bf16 v[2:17], v[206:209], v[54:57], v[2:17]
	ds_read2_b64 v[206:209], v247 offset0:136 offset1:138
	v_cvt_pk_bf16_f32 v70, v74, v75
	v_cvt_pk_bf16_f32 v71, v76, v77
	v_cvt_pk_bf16_f32 v72, v78, v79
	s_waitcnt lgkmcnt(1)
	v_mfma_f32_32x32x16_bf16 v[18:33], v[210:213], v[54:57], v[18:33]
	ds_read2_b64 v[210:213], v0 offset0:168 offset1:170
	v_cvt_pk_bf16_f32 v73, v80, v81
	v_mfma_f32_4x4x4_16b_bf16 v[34:37], v[118:119], v[54:55], v[34:37]
	v_mfma_f32_4x4x4_16b_bf16 v[38:41], v[118:119], v[56:57], v[38:41]
	s_waitcnt vmcnt(1)
	ds_write_b128 v201, v[98:101] offset:0
	s_waitcnt vmcnt(0)
	ds_write2_b64 v127, v[102:103], v[104:105] offset1:1
	s_waitcnt lgkmcnt(3)
	v_mfma_f32_32x32x16_bf16 v[2:17], v[206:209], v[66:69], v[2:17]
	ds_read2_b64 v[206:209], v247 offset0:140 offset1:142
	v_exp_f32_e32 v214, v214
	v_exp_f32_e32 v215, v215
	v_exp_f32_e32 v216, v216
	s_waitcnt lgkmcnt(3)
	v_mfma_f32_32x32x16_bf16 v[18:33], v[210:213], v[66:69], v[18:33]
	ds_read2_b64 v[210:213], v0 offset0:172 offset1:174
	v_exp_f32_e32 v217, v217
	v_exp_f32_e32 v218, v218
	v_mfma_f32_4x4x4_16b_bf16 v[34:37], v[118:119], v[66:67], v[34:37]
	v_mfma_f32_4x4x4_16b_bf16 v[38:41], v[118:119], v[68:69], v[38:41]
	s_waitcnt lgkmcnt(1)
	v_mfma_f32_32x32x16_bf16 v[2:17], v[206:209], v[70:73], v[2:17]
	v_exp_f32_e32 v219, v219
	v_exp_f32_e32 v220, v220
	v_exp_f32_e32 v221, v221
	s_waitcnt lgkmcnt(0)
	v_mfma_f32_32x32x16_bf16 v[18:33], v[210:213], v[70:73], v[18:33]
	v_cvt_pk_bf16_f32 v214, v214, v215
	v_cvt_pk_bf16_f32 v215, v216, v217
	v_cvt_pk_bf16_f32 v216, v218, v219
	v_mfma_f32_4x4x4_16b_bf16 v[34:37], v[118:119], v[70:71], v[34:37]
	v_mfma_f32_4x4x4_16b_bf16 v[38:41], v[118:119], v[72:73], v[38:41]
	v_cvt_pk_bf16_f32 v217, v220, v221
	s_waitcnt lgkmcnt(0)
	s_barrier
; #define LAS __attribute__((address_space(3)))
; template <bool TRACK> ...
;     ...
;             for (int d = 0; d < 4; ++d) { kf[2 * d] = *(const LAS bf16x8*)(Kbuf + (r32 * 72 + d * 16 + hi * 8) * 2); kf[2 * d + 1] = *(const LAS bf16x8*)(Kbuf + ((32 + r32) * 72 + d * 16 + hi * 8) * 2); }
;             __builtin_amdgcn_sched_barrier(0);
; #pragma unroll
;             for (int d = 0; d < 4; ++d) {
;                 s0 = __builtin_amdgcn_mfma_f32_32x32x16_bf16(kf[2 * d], qf[d], s0, 0, 0, 0);
;                 s1 = __builtin_amdgcn_mfma_f32_32x32x16_bf16(kf[2 * d + 1], qf[d], s1, 0, 0, 0);
;             }
; #pragma unroll
;             for (int kc = 0; kc < 2; ++kc) {
;                 const LAS unsigned char* vp0 = Vbuf + (r32 * 68 + kc * 16 + 4 * hi) * 2; const LAS unsigned char* vp1 = vp0 + 32 * 68 * 2;
;                 vq[4 * kc] = *(const LAS u32x2*)vp0; vq[4 * kc + 1] = *(const LAS u32x2*)(vp0 + 16); vq[4 * kc + 2] = *(const LAS u32x2*)vp1; vq[4 * kc + 3] = *(const LAS u32x2*)(vp1 + 16); }
;             __builtin_amdgcn_sched_barrier(0);
;             } else {
; #pragma unroll
;             for (int d = 0; d < 4; ++d) {
;                 const bf16x8 a0 = *(const LAS bf16x8*)(Kbuf + (r32 * 72 + d * 16 + hi * 8) * 2);
;                 const bf16x8 a1 = *(const LAS bf16x8*)(Kbuf + ((32 + r32) * 72 + d * 16 + hi * 8) * 2);
;                 s0 = __builtin_amdgcn_mfma_f32_32x32x16_bf16(a0, qf[d], s0, 0, 0, 0);
;                 s1 = __builtin_amdgcn_mfma_f32_32x32x16_bf16(a1, qf[d], s1, 0, 0, 0);
;             }
;             }
;             if (mt) { const int qpos = qstart + wave * 32 + r32;
; #pragma unroll
;                 for (int r = 0; r < 16; ++r) { const int d0 = qpos - (kpos0 + crow(r, hi)); if (d0 > 128 || d0 < -128) s0[r] = -INFINITY; const int d1 = d0 - 32; if (d1 > 128 || d1 < -128) s1[r] = -INFINITY; } }
;             if (TRACK) {
;             float mx = fmaxf(fmaxf(s0[0], s1[0]), s0[1]);
; #pragma unroll
;             for (int r = 1; r < 15; r += 2) mx = fmaxf(fmaxf(mx, s1[r]), fmaxf(fmaxf(s0[r + 1], s1[r + 1]), s0[r + 2 < 16 ? r + 2 : 15]));
;             mx = fmaxf(mx, s1[15]);
;             mx = fmaxf(mx, __shfl_xor(mx, 32));
;             if (__any(mx > ATT_THR)) {
;                 const float dl = fmaxf(mx, 0.f); m += dl; const float alpha = __builtin_amdgcn_exp2f(-dl); lsum *= alpha;
; #pragma unroll
	global_load_dwordx4 v[98:101], v[114:115], off
	global_load_dwordx4 v[102:105], v[116:117], off
	ds_read_b128 v[106:109], v204 offset:0
	ds_read_b128 v[110:113], v202 offset:0
	ds_read_b128 v[158:161], v204 offset:32
	ds_read2_b64 v[206:209], v123 offset0:128 offset1:130
	ds_read2_b64 v[210:213], v125 offset0:160 offset1:162
	v_lshl_add_u64 v[114:115], v[114:115], 0, s[4:5]
	v_lshl_add_u64 v[116:117], v[116:117], 0, s[38:39]
	s_waitcnt lgkmcnt(4)
	v_mfma_f32_32x32x16_bf16 v[50:65], v[106:109], v[94:97], 0
	ds_read_b128 v[106:109], v202 offset:32
	v_exp_f32_e32 v222, v222
	v_exp_f32_e32 v223, v223
	v_exp_f32_e32 v224, v224
	s_waitcnt lgkmcnt(4)
	v_mfma_f32_32x32x16_bf16 v[66:81], v[110:113], v[94:97], 0
	ds_read_b128 v[110:113], v204 offset:64
	v_exp_f32_e32 v225, v225
	v_exp_f32_e32 v226, v226
	v_exp_f32_e32 v227, v227
	s_waitcnt lgkmcnt(4)
	v_mfma_f32_32x32x16_bf16 v[50:65], v[158:161], v[90:93], v[50:65]
	ds_read_b128 v[158:161], v202 offset:64
	v_exp_f32_e32 v228, v228
	v_exp_f32_e32 v229, v229
	v_cvt_pk_bf16_f32 v218, v222, v223
	s_waitcnt lgkmcnt(2)
	v_mfma_f32_32x32x16_bf16 v[66:81], v[106:109], v[90:93], v[66:81]
	ds_read_b128 v[106:109], v204 offset:96
	v_cvt_pk_bf16_f32 v219, v224, v225
	v_cvt_pk_bf16_f32 v220, v226, v227
	v_cvt_pk_bf16_f32 v221, v228, v229
	s_waitcnt lgkmcnt(2)
	v_mfma_f32_32x32x16_bf16 v[50:65], v[110:113], v[86:89], v[50:65]
	ds_read_b128 v[110:113], v202 offset:96
	v_exp_f32_e32 v230, v230
	v_exp_f32_e32 v231, v231
	v_exp_f32_e32 v232, v232
	s_waitcnt lgkmcnt(2)
	v_mfma_f32_32x32x16_bf16 v[66:81], v[158:161], v[86:89], v[66:81]
	v_exp_f32_e32 v233, v233
	v_exp_f32_e32 v234, v234
	v_exp_f32_e32 v235, v235
	s_waitcnt lgkmcnt(1)
	v_mfma_f32_32x32x16_bf16 v[50:65], v[106:109], v[82:85], v[50:65]
	v_exp_f32_e32 v236, v236
	v_exp_f32_e32 v237, v237
	v_cvt_pk_bf16_f32 v230, v230, v231
	s_waitcnt lgkmcnt(0)
	v_mfma_f32_32x32x16_bf16 v[66:81], v[110:113], v[82:85], v[66:81]
	v_cvt_pk_bf16_f32 v231, v232, v233
	v_cvt_pk_bf16_f32 v232, v234, v235
	v_cvt_pk_bf16_f32 v233, v236, v237
	v_mfma_f32_32x32x16_bf16 v[2:17], v[206:209], v[214:217], v[2:17]
	ds_read2_b64 v[206:209], v123 offset0:132 offset1:134
	v_exp_f32_e32 v238, v238
	v_exp_f32_e32 v239, v239
	v_exp_f32_e32 v240, v240
	v_mfma_f32_32x32x16_bf16 v[18:33], v[210:213], v[214:217], v[18:33]
	ds_read2_b64 v[210:213], v125 offset0:164 offset1:166
	v_exp_f32_e32 v241, v241
	v_exp_f32_e32 v242, v242
	v_exp_f32_e32 v243, v243
	v_mfma_f32_4x4x4_16b_bf16 v[34:37], v[118:119], v[214:215], v[34:37]
	v_mfma_f32_4x4x4_16b_bf16 v[38:41], v[118:119], v[216:217], v[38:41]
	v_exp_f32_e32 v244, v244
	v_exp_f32_e32 v245, v245
	s_waitcnt lgkmcnt(1)
	v_mfma_f32_32x32x16_bf16 v[2:17], v[206:209], v[218:221], v[2:17]
	ds_read2_b64 v[206:209], v123 offset0:136 offset1:138
	v_cvt_pk_bf16_f32 v234, v238, v239
	v_cvt_pk_bf16_f32 v235, v240, v241
	v_cvt_pk_bf16_f32 v236, v242, v243
	s_waitcnt lgkmcnt(1)
	v_mfma_f32_32x32x16_bf16 v[18:33], v[210:213], v[218:221], v[18:33]
	ds_read2_b64 v[210:213], v125 offset0:168 offset1:170
	v_cvt_pk_bf16_f32 v237, v244, v245
	v_mfma_f32_4x4x4_16b_bf16 v[34:37], v[118:119], v[218:219], v[34:37]
	v_mfma_f32_4x4x4_16b_bf16 v[38:41], v[118:119], v[220:221], v[38:41]
	s_waitcnt vmcnt(1)
	ds_write_b128 v201, v[98:101] offset:18432
	s_waitcnt vmcnt(0)
	ds_write2_b64 v129, v[102:103], v[104:105] offset1:1
	s_waitcnt lgkmcnt(3)
	v_mfma_f32_32x32x16_bf16 v[2:17], v[206:209], v[230:233], v[2:17]
	ds_read2_b64 v[206:209], v123 offset0:140 offset1:142
	v_exp_f32_e32 v50, v50
	v_exp_f32_e32 v51, v51
	v_exp_f32_e32 v52, v52
	s_waitcnt lgkmcnt(3)
	v_mfma_f32_32x32x16_bf16 v[18:33], v[210:213], v[230:233], v[18:33]
	ds_read2_b64 v[210:213], v125 offset0:172 offset1:174
	v_exp_f32_e32 v53, v53
	v_exp_f32_e32 v54, v54
	v_mfma_f32_4x4x4_16b_bf16 v[34:37], v[118:119], v[230:231], v[34:37]
	v_mfma_f32_4x4x4_16b_bf16 v[38:41], v[118:119], v[232:233], v[38:41]
	s_waitcnt lgkmcnt(1)
	v_mfma_f32_32x32x16_bf16 v[2:17], v[206:209], v[234:237], v[2:17]
	v_exp_f32_e32 v55, v55
	v_exp_f32_e32 v56, v56
	v_exp_f32_e32 v57, v57
	s_waitcnt lgkmcnt(0)
	v_mfma_f32_32x32x16_bf16 v[18:33], v[210:213], v[234:237], v[18:33]
	v_cvt_pk_bf16_f32 v50, v50, v51
	v_cvt_pk_bf16_f32 v51, v52, v53
	v_cvt_pk_bf16_f32 v52, v54, v55
	v_mfma_f32_4x4x4_16b_bf16 v[34:37], v[118:119], v[234:235], v[34:37]
	v_mfma_f32_4x4x4_16b_bf16 v[38:41], v[118:119], v[236:237], v[38:41]
	v_cvt_pk_bf16_f32 v53, v56, v57
	s_add_i32 s20, s20, 2
	s_cmp_lg_u32 s20, 36
	s_waitcnt lgkmcnt(0)
	s_barrier
	s_cbranch_scc1 .LBB0_167
	s_nop 15
	v_readlane_b32 s89, v248, 3
	v_add_f32_e32 v34, v34, v38
	s_nop 0
	ds_bpermute_b32 v35, v188, v34
	s_waitcnt lgkmcnt(0)
	v_add_f32_e32 v34, v34, v35
	s_nop 0
	v_div_scale_f32 v0, s[20:21], v34, v34, 1.0
	v_rcp_f32_e32 v35, v0
	s_waitcnt lgkmcnt(0)
	s_barrier
; #define LAS __attribute__((address_space(3)))
; __device__ __forceinline__ unsigned pk2(float lo, float hi) { f32x2_t v = {lo, hi}; bf16x2_t b = __builtin_convertvector(v, bf16x2_t); return __builtin_bit_cast(unsigned, b); }
; __device__ __forceinline__ float silu_f(float v) { return v * __builtin_amdgcn_rcpf(1.0f + __expf(-v)); }
; template <bool TRACK> ...
;     ...
;     const float ltot = TRACK ? lsum + __shfl_xor(lsum, 32) : lacc[0]; const float inv = 1.0f / ltot;
;     {
;         LAS unsigned char* scr = lds + 40960 + wave * 8704;
; #pragma unroll
;         for (int dh = 0; dh < 2; ++dh)
; #pragma unroll
;             for (int rg = 0; rg < 4; ++rg) { const int d = dh * 32 + 8 * rg + 4 * hi;
;                 f32x4 ov; ov.x = (dh == 0 ? o0[4 * rg] : o1[4 * rg]) * inv; ov.y = (dh == 0 ? o0[4 * rg + 1] : o1[4 * rg + 1]) * inv; ov.z = (dh == 0 ? o0[4 * rg + 2] : o1[4 * rg + 2]) * inv; ov.w = (dh == 0 ? o0[4 * rg + 3] : o1[4 * rg + 3]) * inv;
;                 *(LAS f32x4*)(scr + r32 * 272 + d * 4) = ov; }
;         const int pc = lane & 7;
; #pragma unroll
;         for (int i = 0; i < 4; ++i) { const int rw = i * 8 + (lane >> 3), row = wave * 32 + rw;
;             const f32x4 oa = *(const LAS f32x4*)(scr + rw * 272 + pc * 32), ob = *(const LAS f32x4*)(scr + rw * 272 + pc * 32 + 16);
;             float gv[8]; unpack8(*(const u32x4*)(gate + (size_t)row * INW + 8 * pc), gv);
;             u32x4 w; w.x = pk2(oa.x * silu_f(gv[0]), oa.y * silu_f(gv[1])); w.y = pk2(oa.z * silu_f(gv[2]), oa.w * silu_f(gv[3]));
;             w.z = pk2(ob.x * silu_f(gv[4]), ob.y * silu_f(gv[5])); w.w = pk2(ob.z * silu_f(gv[6]), ob.w * silu_f(gv[7]));
;             *(u32x4*)(outp + (size_t)row * DM + 8 * pc) = w; }
	v_fma_f32 v36, -v0, v35, 1.0
	v_fmac_f32_e32 v35, v36, v35
	v_div_scale_f32 v36, vcc, 1.0, v34, 1.0
	v_mul_f32_e32 v37, v36, v35
	v_fma_f32 v38, -v0, v37, v36
	v_fmac_f32_e32 v37, v38, v35
	v_fma_f32 v0, -v0, v37, v36
	v_div_fmas_f32 v0, v0, v35, v37
	v_div_fixup_f32 v0, v0, v34, 1.0
	s_nop 1
	v_mul_f32_e64 v2, v2, v0
	v_mul_f32_e64 v3, v3, v0
	v_pk_mul_f32 v[4:5], v[4:5], v[0:1] op_sel_hi:[1,0]
	v_add_u32_e32 v34, v198, v156
	ds_write_b128 v34, v[2:5] offset:40960
	v_pk_mul_f32 v[2:3], v[6:7], v[0:1] op_sel_hi:[1,0]
	v_pk_mul_f32 v[4:5], v[8:9], v[0:1] op_sel_hi:[1,0]
	ds_write_b128 v34, v[2:5] offset:40992
	v_pk_mul_f32 v[2:3], v[10:11], v[0:1] op_sel_hi:[1,0]
	v_pk_mul_f32 v[4:5], v[12:13], v[0:1] op_sel_hi:[1,0]
	ds_write_b128 v34, v[2:5] offset:41024
	v_pk_mul_f32 v[2:3], v[14:15], v[0:1] op_sel_hi:[1,0]
	v_pk_mul_f32 v[4:5], v[16:17], v[0:1] op_sel_hi:[1,0]
	ds_write_b128 v34, v[2:5] offset:41056
	v_pk_mul_f32 v[2:3], v[18:19], v[0:1] op_sel_hi:[1,0]
	v_pk_mul_f32 v[4:5], v[20:21], v[0:1] op_sel_hi:[1,0]
	ds_write_b128 v34, v[2:5] offset:41088
	v_pk_mul_f32 v[2:3], v[22:23], v[0:1] op_sel_hi:[1,0]
	v_pk_mul_f32 v[4:5], v[24:25], v[0:1] op_sel_hi:[1,0]
	ds_write_b128 v34, v[2:5] offset:41120
	v_pk_mul_f32 v[2:3], v[26:27], v[0:1] op_sel_hi:[1,0]
	v_pk_mul_f32 v[4:5], v[28:29], v[0:1] op_sel_hi:[1,0]
	ds_write_b128 v34, v[2:5] offset:41152
	v_pk_mul_f32 v[2:3], v[30:31], v[0:1] op_sel_hi:[1,0]
	v_pk_mul_f32 v[4:5], v[32:33], v[0:1] op_sel_hi:[1,0]
	ds_write_b128 v34, v[2:5] offset:41184
	v_add_u32_e32 v0, v192, v193
	ds_read_b128 v[6:9], v0 offset:40960
	ds_read_b128 v[2:5], v0 offset:40976
	global_load_dwordx4 v[10:13], v[154:155], off offset:1280
	s_waitcnt vmcnt(0)
	v_lshlrev_b32_e32 v14, 16, v10
	v_and_b32_e32 v15, 0xffff0000, v10
	v_mul_f32_e32 v10, 0xbfb8aa3b, v14
	v_exp_f32_e32 v10, v10
	s_nop 0
	v_add_f32_e32 v10, 1.0, v10
	v_rcp_f32_e32 v16, v10
	v_mul_f32_e32 v10, 0xbfb8aa3b, v15
	v_exp_f32_e32 v10, v10
	s_nop 0
	v_add_f32_e32 v10, 1.0, v10
	v_rcp_f32_e32 v17, v10
	v_lshlrev_b32_e32 v10, 16, v11
	v_and_b32_e32 v11, 0xffff0000, v11
	v_pk_mul_f32 v[14:15], v[16:17], v[14:15]
	s_waitcnt lgkmcnt(1)
	v_pk_mul_f32 v[6:7], v[6:7], v[14:15]
	s_nop 0
	v_cvt_pk_bf16_f32 v6, v6, v7
	v_mul_f32_e32 v7, 0xbfb8aa3b, v10
	v_exp_f32_e32 v7, v7
	s_nop 0
	v_add_f32_e32 v7, 1.0, v7
	v_rcp_f32_e32 v14, v7
	v_mul_f32_e32 v7, 0xbfb8aa3b, v11
	v_exp_f32_e32 v7, v7
	s_nop 0
	v_add_f32_e32 v7, 1.0, v7
	v_rcp_f32_e32 v15, v7
	s_nop 0
	v_pk_mul_f32 v[10:11], v[14:15], v[10:11]
	s_nop 0
	v_pk_mul_f32 v[8:9], v[8:9], v[10:11]
	s_nop 0
	v_cvt_pk_bf16_f32 v7, v8, v9
	v_lshlrev_b32_e32 v8, 16, v12
	v_and_b32_e32 v9, 0xffff0000, v12
	v_mul_f32_e32 v10, 0xbfb8aa3b, v8
	v_mul_f32_e32 v11, 0xbfb8aa3b, v9
	v_exp_f32_e32 v10, v10
	v_exp_f32_e32 v11, v11
	v_add_f32_e32 v10, 1.0, v10
	v_add_f32_e32 v11, 1.0, v11
	v_rcp_f32_e32 v10, v10
	v_rcp_f32_e32 v11, v11
	s_nop 0
	v_pk_mul_f32 v[8:9], v[10:11], v[8:9]
	s_waitcnt lgkmcnt(0)
	v_pk_mul_f32 v[2:3], v[2:3], v[8:9]
	s_nop 0
	v_cvt_pk_bf16_f32 v8, v2, v3
	v_lshlrev_b32_e32 v2, 16, v13
	v_mul_f32_e32 v9, 0xbfb8aa3b, v2
	v_exp_f32_e32 v9, v9
	v_and_b32_e32 v3, 0xffff0000, v13
	v_add_f32_e32 v9, 1.0, v9
	v_rcp_f32_e32 v10, v9
	v_mul_f32_e32 v9, 0xbfb8aa3b, v3
	v_exp_f32_e32 v9, v9
	s_nop 0
	v_add_f32_e32 v9, 1.0, v9
	v_rcp_f32_e32 v11, v9
	s_nop 0
	v_pk_mul_f32 v[2:3], v[10:11], v[2:3]
	s_nop 0
	v_pk_mul_f32 v[2:3], v[4:5], v[2:3]
	s_nop 0
	v_cvt_pk_bf16_f32 v9, v2, v3
	global_store_dwordx4 v[152:153], v[6:9], off
	ds_read_b128 v[6:9], v0 offset:43136
	ds_read_b128 v[2:5], v0 offset:43152
	global_load_dwordx4 v[10:13], v[150:151], off offset:1280
	s_waitcnt vmcnt(0)
	v_lshlrev_b32_e32 v14, 16, v10
	v_and_b32_e32 v15, 0xffff0000, v10
	v_mul_f32_e32 v10, 0xbfb8aa3b, v14
	v_exp_f32_e32 v10, v10
	s_nop 0
	v_add_f32_e32 v10, 1.0, v10
	v_rcp_f32_e32 v16, v10
	v_mul_f32_e32 v10, 0xbfb8aa3b, v15
	v_exp_f32_e32 v10, v10
	s_nop 0
	v_add_f32_e32 v10, 1.0, v10
	v_rcp_f32_e32 v17, v10
	v_lshlrev_b32_e32 v10, 16, v11
	v_and_b32_e32 v11, 0xffff0000, v11
	v_pk_mul_f32 v[14:15], v[16:17], v[14:15]
	s_waitcnt lgkmcnt(1)
	v_pk_mul_f32 v[6:7], v[6:7], v[14:15]
	s_nop 0
	v_cvt_pk_bf16_f32 v6, v6, v7
	v_mul_f32_e32 v7, 0xbfb8aa3b, v10
	v_exp_f32_e32 v7, v7
	s_nop 0
	v_add_f32_e32 v7, 1.0, v7
	v_rcp_f32_e32 v14, v7
	v_mul_f32_e32 v7, 0xbfb8aa3b, v11
	v_exp_f32_e32 v7, v7
	s_nop 0
	v_add_f32_e32 v7, 1.0, v7
	v_rcp_f32_e32 v15, v7
	s_nop 0
	v_pk_mul_f32 v[10:11], v[14:15], v[10:11]
	s_nop 0
	v_pk_mul_f32 v[8:9], v[8:9], v[10:11]
	s_nop 0
	v_cvt_pk_bf16_f32 v7, v8, v9
	v_lshlrev_b32_e32 v8, 16, v12
	v_and_b32_e32 v9, 0xffff0000, v12
	v_mul_f32_e32 v10, 0xbfb8aa3b, v8
	v_mul_f32_e32 v11, 0xbfb8aa3b, v9
	v_exp_f32_e32 v10, v10
	v_exp_f32_e32 v11, v11
	v_add_f32_e32 v10, 1.0, v10
	v_add_f32_e32 v11, 1.0, v11
	v_rcp_f32_e32 v10, v10
	v_rcp_f32_e32 v11, v11
	s_nop 0
	v_pk_mul_f32 v[8:9], v[10:11], v[8:9]
	s_waitcnt lgkmcnt(0)
; #define LAS __attribute__((address_space(3)))
; __device__ __forceinline__ unsigned pk2(float lo, float hi) { f32x2_t v = {lo, hi}; bf16x2_t b = __builtin_convertvector(v, bf16x2_t); return __builtin_bit_cast(unsigned, b); }
; __device__ __forceinline__ float silu_f(float v) { return v * __builtin_amdgcn_rcpf(1.0f + __expf(-v)); }
; template <bool TRACK> ...
;     ...
;         const int pc = lane & 7;
; #pragma unroll
;         for (int i = 0; i < 4; ++i) { const int rw = i * 8 + (lane >> 3), row = wave * 32 + rw;
;             const f32x4 oa = *(const LAS f32x4*)(scr + rw * 272 + pc * 32), ob = *(const LAS f32x4*)(scr + rw * 272 + pc * 32 + 16);
;             float gv[8]; unpack8(*(const u32x4*)(gate + (size_t)row * INW + 8 * pc), gv);
;             u32x4 w; w.x = pk2(oa.x * silu_f(gv[0]), oa.y * silu_f(gv[1])); w.y = pk2(oa.z * silu_f(gv[2]), oa.w * silu_f(gv[3]));
;             w.z = pk2(ob.x * silu_f(gv[4]), ob.y * silu_f(gv[5])); w.w = pk2(ob.z * silu_f(gv[6]), ob.w * silu_f(gv[7]));
;             *(u32x4*)(outp + (size_t)row * DM + 8 * pc) = w; }
	v_pk_mul_f32 v[2:3], v[2:3], v[8:9]
	s_nop 0
	v_cvt_pk_bf16_f32 v8, v2, v3
	v_lshlrev_b32_e32 v2, 16, v13
	v_mul_f32_e32 v9, 0xbfb8aa3b, v2
	v_exp_f32_e32 v9, v9
	v_and_b32_e32 v3, 0xffff0000, v13
	v_add_f32_e32 v9, 1.0, v9
	v_rcp_f32_e32 v10, v9
	v_mul_f32_e32 v9, 0xbfb8aa3b, v3
	v_exp_f32_e32 v9, v9
	s_nop 0
	v_add_f32_e32 v9, 1.0, v9
	v_rcp_f32_e32 v11, v9
	s_nop 0
	v_pk_mul_f32 v[2:3], v[10:11], v[2:3]
	s_nop 0
	v_pk_mul_f32 v[2:3], v[4:5], v[2:3]
	s_nop 0
	v_cvt_pk_bf16_f32 v9, v2, v3
	global_store_dwordx4 v[144:145], v[6:9], off
	ds_read_b128 v[6:9], v0 offset:45312
	ds_read_b128 v[2:5], v0 offset:45328
	global_load_dwordx4 v[10:13], v[142:143], off offset:1280
	s_waitcnt vmcnt(0)
	v_lshlrev_b32_e32 v14, 16, v10
	v_and_b32_e32 v15, 0xffff0000, v10
	v_mul_f32_e32 v10, 0xbfb8aa3b, v14
	v_exp_f32_e32 v10, v10
	s_nop 0
	v_add_f32_e32 v10, 1.0, v10
	v_rcp_f32_e32 v16, v10
	v_mul_f32_e32 v10, 0xbfb8aa3b, v15
	v_exp_f32_e32 v10, v10
	s_nop 0
	v_add_f32_e32 v10, 1.0, v10
	v_rcp_f32_e32 v17, v10
	v_lshlrev_b32_e32 v10, 16, v11
	v_and_b32_e32 v11, 0xffff0000, v11
	v_pk_mul_f32 v[14:15], v[16:17], v[14:15]
	s_waitcnt lgkmcnt(1)
	v_pk_mul_f32 v[6:7], v[6:7], v[14:15]
	s_nop 0
	v_cvt_pk_bf16_f32 v6, v6, v7
	v_mul_f32_e32 v7, 0xbfb8aa3b, v10
	v_exp_f32_e32 v7, v7
	s_nop 0
	v_add_f32_e32 v7, 1.0, v7
	v_rcp_f32_e32 v14, v7
	v_mul_f32_e32 v7, 0xbfb8aa3b, v11
	v_exp_f32_e32 v7, v7
	s_nop 0
	v_add_f32_e32 v7, 1.0, v7
	v_rcp_f32_e32 v15, v7
	s_nop 0
	v_pk_mul_f32 v[10:11], v[14:15], v[10:11]
	s_nop 0
	v_pk_mul_f32 v[8:9], v[8:9], v[10:11]
	s_nop 0
	v_cvt_pk_bf16_f32 v7, v8, v9
	v_lshlrev_b32_e32 v8, 16, v12
	v_and_b32_e32 v9, 0xffff0000, v12
	v_mul_f32_e32 v10, 0xbfb8aa3b, v8
	v_mul_f32_e32 v11, 0xbfb8aa3b, v9
	v_exp_f32_e32 v10, v10
	v_exp_f32_e32 v11, v11
	v_add_f32_e32 v10, 1.0, v10
	v_add_f32_e32 v11, 1.0, v11
	v_rcp_f32_e32 v10, v10
	v_rcp_f32_e32 v11, v11
	s_nop 0
	v_pk_mul_f32 v[8:9], v[10:11], v[8:9]
	s_waitcnt lgkmcnt(0)
	v_pk_mul_f32 v[2:3], v[2:3], v[8:9]
	s_nop 0
	v_cvt_pk_bf16_f32 v8, v2, v3
	v_lshlrev_b32_e32 v2, 16, v13
	v_mul_f32_e32 v9, 0xbfb8aa3b, v2
	v_exp_f32_e32 v9, v9
	v_and_b32_e32 v3, 0xffff0000, v13
	v_add_f32_e32 v9, 1.0, v9
	v_rcp_f32_e32 v10, v9
	v_mul_f32_e32 v9, 0xbfb8aa3b, v3
	v_exp_f32_e32 v9, v9
	s_nop 0
	v_add_f32_e32 v9, 1.0, v9
	v_rcp_f32_e32 v11, v9
	s_nop 0
	v_pk_mul_f32 v[2:3], v[10:11], v[2:3]
	s_nop 0
	v_pk_mul_f32 v[2:3], v[4:5], v[2:3]
	s_nop 0
	v_cvt_pk_bf16_f32 v9, v2, v3
	global_store_dwordx4 v[140:141], v[6:9], off
	ds_read_b128 v[6:9], v0 offset:47488
	ds_read_b128 v[2:5], v0 offset:47504
	global_load_dwordx4 v[10:13], v[138:139], off offset:1280
	s_waitcnt vmcnt(0)
	v_lshlrev_b32_e32 v14, 16, v10
	v_mul_f32_e32 v0, 0xbfb8aa3b, v14
	v_exp_f32_e32 v0, v0
	v_and_b32_e32 v15, 0xffff0000, v10
	v_lshlrev_b32_e32 v10, 16, v11
	v_and_b32_e32 v11, 0xffff0000, v11
	v_add_f32_e32 v0, 1.0, v0
	v_rcp_f32_e32 v16, v0
	v_mul_f32_e32 v0, 0xbfb8aa3b, v15
	v_exp_f32_e32 v0, v0
	s_nop 0
	v_add_f32_e32 v0, 1.0, v0
	v_rcp_f32_e32 v17, v0
	v_mul_f32_e32 v0, 0xbfb8aa3b, v10
	v_exp_f32_e32 v0, v0
	v_pk_mul_f32 v[14:15], v[16:17], v[14:15]
	s_waitcnt lgkmcnt(1)
	v_pk_mul_f32 v[6:7], v[6:7], v[14:15]
	v_add_f32_e32 v0, 1.0, v0
	v_rcp_f32_e32 v14, v0
	v_mul_f32_e32 v0, 0xbfb8aa3b, v11
	v_exp_f32_e32 v0, v0
	v_cvt_pk_bf16_f32 v6, v6, v7
	v_add_f32_e32 v0, 1.0, v0
	v_rcp_f32_e32 v15, v0
	s_nop 0
	v_pk_mul_f32 v[10:11], v[14:15], v[10:11]
	s_nop 0
	v_pk_mul_f32 v[8:9], v[8:9], v[10:11]
	s_nop 0
	v_cvt_pk_bf16_f32 v7, v8, v9
	v_lshlrev_b32_e32 v8, 16, v12
	v_mul_f32_e32 v0, 0xbfb8aa3b, v8
	v_exp_f32_e32 v0, v0
	v_and_b32_e32 v9, 0xffff0000, v12
	v_add_f32_e32 v0, 1.0, v0
	v_rcp_f32_e32 v10, v0
	v_mul_f32_e32 v0, 0xbfb8aa3b, v9
	v_exp_f32_e32 v0, v0
	s_nop 0
	v_add_f32_e32 v0, 1.0, v0
	v_rcp_f32_e32 v11, v0
	s_nop 0
	v_pk_mul_f32 v[8:9], v[10:11], v[8:9]
	s_waitcnt lgkmcnt(0)
	v_pk_mul_f32 v[2:3], v[2:3], v[8:9]
	s_nop 0
	v_cvt_pk_bf16_f32 v8, v2, v3
	v_lshlrev_b32_e32 v2, 16, v13
	v_mul_f32_e32 v0, 0xbfb8aa3b, v2
	v_exp_f32_e32 v0, v0
	v_and_b32_e32 v3, 0xffff0000, v13
	v_add_f32_e32 v0, 1.0, v0
	v_rcp_f32_e32 v10, v0
	v_mul_f32_e32 v0, 0xbfb8aa3b, v3
	v_exp_f32_e32 v0, v0
	s_nop 0
	v_add_f32_e32 v0, 1.0, v0
	v_rcp_f32_e32 v11, v0
	s_nop 0
	v_pk_mul_f32 v[2:3], v[10:11], v[2:3]
	s_nop 0
	v_pk_mul_f32 v[2:3], v[4:5], v[2:3]
	s_nop 0
	v_cvt_pk_bf16_f32 v9, v2, v3
	global_store_dwordx4 v[136:137], v[6:9], off
